# combined LRU reductions + bwd gate segment with all fragments prefetched (counted waits) and stage-wise gate math
# baseline (speedup 1.0000x reference)
; #define LAS __attribute__((address_space(3)))
; template <int dir>
; __device__ __forceinline__ void lru_pass(LAS unsigned char* lds, const Params& P, int b, int h, int q, bool dry) {
;     ...
;             const int sbase = 32 * wid + 16 * g;
;             { const int sl = 32 * wid + s_i; const int tlA = dir == 0 ? sl : 255 - sl;
;               const LAS unsigned char* ap = XC + tlA * XC_PITCH + 16 * g;
;               const LAS unsigned char* wrp = WB + nl * XC_PITCH + 16 * g; const LAS unsigned char* wip = wrp + 32 * XC_PITCH;
; #pragma unroll
;               for (int ks = 0; ks < 8; ++ks) { const bf16x8 A = *(const LAS bf16x8*)(ap + 32 * ks);
;                   const bf16x8 Br = *(const LAS bf16x8*)(wrp + 32 * ks), Bi = *(const LAS bf16x8*)(wip + 32 * ks);
;                   zr = __builtin_amdgcn_mfma_f32_32x32x16_bf16(A, Br, zr, 0, 0, 0); zi = __builtin_amdgcn_mfma_f32_32x32x16_bf16(A, Bi, zi, 0, 0, 0); } }
;             unsigned xcb[16], pk[16];
; #pragma unroll
;             for (int v = 0; v < 16; ++v) { const int s = sbase + v; const int tl = dir == 0 ? s : 255 - s; xcb[v] = *(const LAS bf16_t*)(XC + tl * XC_PITCH + chl * 2);
;                 if (dir == 0) pk[v] = *(const LAS bf16_t*)(TIN + tl * IO_NP + nl * 2); else pk[v] = *(const LAS unsigned*)(TIN + tl * IO_WP + nl * 4); }
;             float Pp = 1.f, E = 0.f;
; #pragma unroll
;             for (int v = 0; v < 16; ++v) {
;                 const float xcv = __uint_as_float(xcb[v] << 16);
;                 const float r = __builtin_amdgcn_rcpf(1.0f + __builtin_amdgcn_exp2f(zr[v]));
;                 const float ig = __builtin_amdgcn_rcpf(1.0f + __builtin_amdgcn_exp2f(zi[v]));
;                 const float a = __builtin_amdgcn_exp2f(cl * r);
;                 const float sq = __builtin_amdgcn_sqrtf(fmaf(-a, a, 1.0f));
;                 const float u = sq * ig * xcv;
;                 E = fmaf(a, E, u); Pp *= a; zr[v] = E; zi[v] = Pp; }
.LBB0_311:
	ds_read_b128 v[128:131], v172
	ds_read_b128 v[48:51], v173
	ds_read_b128 v[132:135], v172 offset:32
	ds_read_b128 v[52:55], v173 offset:32
	ds_read_b128 v[224:227], v172 offset:64
	ds_read_b128 v[56:59], v173 offset:64
	ds_read_b128 v[228:231], v172 offset:96
	ds_read_b128 v[60:63], v173 offset:96
	ds_read_b128 v[232:235], v172 offset:128
	ds_read_b128 v[236:239], v172 offset:160
	ds_read_b128 v[240:243], v172 offset:192
	ds_read_b128 v[244:247], v172 offset:224
	ds_read_b128 v[248:251], v173 offset:8704
	ds_read_b128 v[146:149], v173 offset:8736
	s_waitcnt lgkmcnt(12)
	v_mfma_f32_32x32x16_bf16 v[32:47], v[128:131], v[48:51], v[0:15]
	ds_read_b128 v[48:51], v173 offset:128
	s_waitcnt lgkmcnt(11)
	v_mfma_f32_32x32x16_bf16 v[32:47], v[132:135], v[52:55], v[32:47]
	ds_read_b128 v[52:55], v173 offset:160
	s_waitcnt lgkmcnt(10)
	v_mfma_f32_32x32x16_bf16 v[32:47], v[224:227], v[56:59], v[32:47]
	ds_read_b128 v[56:59], v173 offset:192
	s_waitcnt lgkmcnt(9)
	v_mfma_f32_32x32x16_bf16 v[32:47], v[228:231], v[60:63], v[32:47]
	ds_read_b128 v[60:63], v173 offset:224
	s_waitcnt lgkmcnt(3)
	v_mfma_f32_32x32x16_bf16 v[32:47], v[232:235], v[48:51], v[32:47]
	s_waitcnt lgkmcnt(2)
	v_mfma_f32_32x32x16_bf16 v[32:47], v[236:239], v[52:55], v[32:47]
	s_waitcnt lgkmcnt(1)
	v_mfma_f32_32x32x16_bf16 v[32:47], v[240:243], v[56:59], v[32:47]
	s_waitcnt lgkmcnt(0)
	v_mfma_f32_32x32x16_bf16 v[32:47], v[244:247], v[60:63], v[32:47]
	v_mfma_f32_32x32x16_bf16 v[48:63], v[128:131], v[248:251], v[16:31]
	ds_read_b128 v[128:131], v173 offset:8768
	s_nop 9
	v_exp_f32_e32 v32, v32
	v_exp_f32_e32 v33, v33
	v_exp_f32_e32 v34, v34
	v_exp_f32_e32 v35, v35
	v_exp_f32_e32 v36, v36
	v_exp_f32_e32 v37, v37
	v_exp_f32_e32 v38, v38
	v_exp_f32_e32 v39, v39
	v_mfma_f32_32x32x16_bf16 v[48:63], v[132:135], v[146:149], v[48:63]
	ds_read_b128 v[132:135], v173 offset:8800
	v_exp_f32_e32 v40, v40
	v_exp_f32_e32 v41, v41
	v_exp_f32_e32 v42, v42
	v_exp_f32_e32 v43, v43
	v_exp_f32_e32 v44, v44
	v_exp_f32_e32 v45, v45
	v_exp_f32_e32 v46, v46
	v_exp_f32_e32 v47, v47
	s_waitcnt lgkmcnt(1)
	v_mfma_f32_32x32x16_bf16 v[48:63], v[224:227], v[128:131], v[48:63]
	ds_read_b128 v[224:227], v173 offset:8832
	v_fma_f32 v32, v32, v159, v159
	v_fma_f32 v33, v33, v159, v159
	v_fma_f32 v34, v34, v159, v159
	v_fma_f32 v35, v35, v159, v159
	v_fma_f32 v36, v36, v159, v159
	v_fma_f32 v37, v37, v159, v159
	v_fma_f32 v38, v38, v159, v159
	v_fma_f32 v39, v39, v159, v159
	s_waitcnt lgkmcnt(1)
	v_mfma_f32_32x32x16_bf16 v[48:63], v[228:231], v[132:135], v[48:63]
	ds_read_b128 v[228:231], v173 offset:8864
	v_fma_f32 v40, v40, v159, v159
	v_fma_f32 v41, v41, v159, v159
	v_fma_f32 v42, v42, v159, v159
	v_fma_f32 v43, v43, v159, v159
	v_fma_f32 v44, v44, v159, v159
	v_fma_f32 v45, v45, v159, v159
	v_fma_f32 v46, v46, v159, v159
	v_fma_f32 v47, v47, v159, v159
	s_waitcnt lgkmcnt(1)
	v_mfma_f32_32x32x16_bf16 v[48:63], v[232:235], v[224:227], v[48:63]
	ds_read_b128 v[128:131], v173 offset:8896
	v_rcp_f32_e32 v32, v32
	v_rcp_f32_e32 v33, v33
	v_rcp_f32_e32 v34, v34
	v_rcp_f32_e32 v35, v35
	v_rcp_f32_e32 v36, v36
	v_rcp_f32_e32 v37, v37
	v_rcp_f32_e32 v38, v38
	v_rcp_f32_e32 v39, v39
	s_waitcnt lgkmcnt(1)
	v_mfma_f32_32x32x16_bf16 v[48:63], v[236:239], v[228:231], v[48:63]
	ds_read_b128 v[132:135], v173 offset:8928
	v_rcp_f32_e32 v40, v40
	v_rcp_f32_e32 v41, v41
	v_rcp_f32_e32 v42, v42
	v_rcp_f32_e32 v43, v43
	v_rcp_f32_e32 v44, v44
	v_rcp_f32_e32 v45, v45
	v_rcp_f32_e32 v46, v46
	v_rcp_f32_e32 v47, v47
	s_waitcnt lgkmcnt(1)
	v_mfma_f32_32x32x16_bf16 v[48:63], v[240:243], v[128:131], v[48:63]
	v_exp_f32_e32 v32, v32
	v_exp_f32_e32 v33, v33
	v_exp_f32_e32 v34, v34
	v_exp_f32_e32 v35, v35
	v_exp_f32_e32 v36, v36
	v_exp_f32_e32 v37, v37
	v_exp_f32_e32 v38, v38
	v_exp_f32_e32 v39, v39
	s_waitcnt lgkmcnt(0)
	v_mfma_f32_32x32x16_bf16 v[48:63], v[244:247], v[132:135], v[48:63]
	v_exp_f32_e32 v40, v40
	v_exp_f32_e32 v41, v41
	v_exp_f32_e32 v42, v42
	v_exp_f32_e32 v43, v43
	v_exp_f32_e32 v44, v44
	v_exp_f32_e32 v45, v45
	v_exp_f32_e32 v46, v46
	v_exp_f32_e32 v47, v47
	ds_read_u16 v162, v174
	ds_read_b32 v226, v175
	ds_read_u16 v163, v176
	ds_read_b32 v225, v177
	ds_read_u16 v232, v178
	ds_read_b32 v224, v179
	ds_read_u16 v233, v180
	ds_read_b32 v223, v181
	ds_read_u16 v234, v182
	ds_read_b32 v135, v183
	ds_read_u16 v235, v184
	ds_read_b32 v134, v185
	ds_read_u16 v236, v186
	ds_read_b32 v133, v187
	ds_read_u16 v237, v188
	ds_read_b32 v131, v189
	ds_read_u16 v146, v190
	ds_read_b32 v132, v191
	ds_read_u16 v147, v192
	ds_read_b32 v130, v193
	ds_read_u16 v148, v194
	ds_read_b32 v129, v195
	ds_read_u16 v149, v196
	ds_read_b32 v128, v197
	ds_read_u16 v239, v198
	ds_read_b32 v67, v199
	ds_read_u16 v240, v200
	ds_read_b32 v66, v201
	ds_read_u16 v241, v202
	ds_read_b32 v64, v203
	ds_read_u16 v242, v204
	ds_read_b32 v251, v205
	v_exp_f32_e32 v48, v48
	v_exp_f32_e32 v49, v49
	v_exp_f32_e32 v50, v50
	v_exp_f32_e32 v51, v51
	v_exp_f32_e32 v52, v52
	v_exp_f32_e32 v53, v53
	v_exp_f32_e32 v54, v54
	v_exp_f32_e32 v55, v55
	v_exp_f32_e32 v56, v56
	v_exp_f32_e32 v57, v57
	v_exp_f32_e32 v58, v58
	v_exp_f32_e32 v59, v59
	v_exp_f32_e32 v60, v60
	v_exp_f32_e32 v61, v61
	v_exp_f32_e32 v62, v62
	v_exp_f32_e32 v63, v63
	v_add_f32_e32 v48, 1.0, v48
	v_add_f32_e32 v49, 1.0, v49
	v_add_f32_e32 v50, 1.0, v50
	v_add_f32_e32 v51, 1.0, v51
	v_add_f32_e32 v52, 1.0, v52
	v_add_f32_e32 v53, 1.0, v53
	v_add_f32_e32 v54, 1.0, v54
	v_add_f32_e32 v55, 1.0, v55
	v_add_f32_e32 v56, 1.0, v56
	v_add_f32_e32 v57, 1.0, v57
	v_add_f32_e32 v58, 1.0, v58
	v_add_f32_e32 v59, 1.0, v59
	v_add_f32_e32 v60, 1.0, v60
	v_add_f32_e32 v61, 1.0, v61
	v_add_f32_e32 v62, 1.0, v62
	v_add_f32_e32 v63, 1.0, v63
	v_rcp_f32_e32 v48, v48
	v_rcp_f32_e32 v49, v49
	v_rcp_f32_e32 v50, v50
	v_rcp_f32_e32 v51, v51
	v_rcp_f32_e32 v52, v52
	v_rcp_f32_e32 v53, v53
	v_rcp_f32_e32 v54, v54
	v_rcp_f32_e32 v55, v55
	v_rcp_f32_e32 v56, v56
	v_rcp_f32_e32 v57, v57
	v_rcp_f32_e32 v58, v58
	v_rcp_f32_e32 v59, v59
	v_rcp_f32_e32 v60, v60
	v_rcp_f32_e32 v61, v61
	v_rcp_f32_e32 v62, v62
	v_rcp_f32_e32 v63, v63
	s_waitcnt lgkmcnt(0)
; template <int dir>
; __device__ __forceinline__ void lru_pass(LAS unsigned char* lds, const Params& P, int b, int h, int q, bool dry) {
;     ...
;             float Pp = 1.f, E = 0.f;
; #pragma unroll
;             for (int v = 0; v < 16; ++v) {
;                 const float xcv = __uint_as_float(xcb[v] << 16);
;                 const float r = __builtin_amdgcn_rcpf(1.0f + __builtin_amdgcn_exp2f(zr[v]));
;                 const float ig = __builtin_amdgcn_rcpf(1.0f + __builtin_amdgcn_exp2f(zi[v]));
;                 const float a = __builtin_amdgcn_exp2f(cl * r);
;                 const float sq = __builtin_amdgcn_sqrtf(fmaf(-a, a, 1.0f));
;                 const float u = sq * ig * xcv;
;                 E = fmaf(a, E, u); Pp *= a; zr[v] = E; zi[v] = Pp; }
;             const float Po = __shfl_xor(Pp, 32), Eo = __shfl_xor(E, 32);
;             const float P0 = g ? Po : Pp, E0 = g ? Eo : E, P1 = g ? Pp : Po, E1 = g ? E : Eo;
;             if (g == 0) { AGG[(wid * 2 + 0) * 32 + nl] = P0 * P1; AGG[(wid * 2 + 1) * 32 + nl] = fmaf(P1, E0, E1); }
	v_fma_f32 v244, -v32, v32, 1.0
	v_fma_f32 v245, -v33, v33, 1.0
	v_fma_f32 v246, -v34, v34, 1.0
	v_fma_f32 v247, -v35, v35, 1.0
	v_sqrt_f32_e32 v244, v244
	v_sqrt_f32_e32 v245, v245
	v_sqrt_f32_e32 v246, v246
	v_sqrt_f32_e32 v247, v247
	v_lshlrev_b32_e32 v162, 16, v162
	v_lshlrev_b32_e32 v163, 16, v163
	v_lshlrev_b32_e32 v232, 16, v232
	v_lshlrev_b32_e32 v233, 16, v233
	v_mul_f32_e32 v244, v244, v48
	v_mul_f32_e32 v245, v245, v49
	v_mul_f32_e32 v246, v246, v50
	v_mul_f32_e32 v247, v247, v51
	v_mul_f32_e32 v49, v244, v162
	v_mul_f32_e32 v228, v245, v163
	v_mul_f32_e32 v229, v246, v232
	v_mul_f32_e32 v230, v247, v233
	v_fma_f32 v244, -v36, v36, 1.0
	v_fma_f32 v245, -v37, v37, 1.0
	v_fma_f32 v246, -v38, v38, 1.0
	v_fma_f32 v247, -v39, v39, 1.0
	v_sqrt_f32_e32 v244, v244
	v_sqrt_f32_e32 v245, v245
	v_sqrt_f32_e32 v246, v246
	v_sqrt_f32_e32 v247, v247
	v_lshlrev_b32_e32 v234, 16, v234
	v_lshlrev_b32_e32 v235, 16, v235
	v_lshlrev_b32_e32 v236, 16, v236
	v_lshlrev_b32_e32 v237, 16, v237
	v_mul_f32_e32 v244, v244, v52
	v_mul_f32_e32 v245, v245, v53
	v_mul_f32_e32 v246, v246, v54
	v_mul_f32_e32 v247, v247, v55
	v_mul_f32_e32 v231, v244, v234
	v_mul_f32_e32 v232, v245, v235
	v_mul_f32_e32 v233, v246, v236
	v_mul_f32_e32 v234, v247, v237
	v_fma_f32 v244, -v40, v40, 1.0
	v_fma_f32 v245, -v41, v41, 1.0
	v_fma_f32 v246, -v42, v42, 1.0
	v_fma_f32 v247, -v43, v43, 1.0
	v_sqrt_f32_e32 v244, v244
	v_sqrt_f32_e32 v245, v245
	v_sqrt_f32_e32 v246, v246
	v_sqrt_f32_e32 v247, v247
	v_lshlrev_b32_e32 v146, 16, v146
	v_lshlrev_b32_e32 v147, 16, v147
	v_lshlrev_b32_e32 v148, 16, v148
	v_lshlrev_b32_e32 v149, 16, v149
	v_mul_f32_e32 v244, v244, v56
	v_mul_f32_e32 v245, v245, v57
	v_mul_f32_e32 v246, v246, v58
	v_mul_f32_e32 v247, v247, v59
	v_mul_f32_e32 v235, v244, v146
	v_mul_f32_e32 v236, v245, v147
	v_mul_f32_e32 v237, v246, v148
	v_mul_f32_e32 v238, v247, v149
	v_fma_f32 v244, -v44, v44, 1.0
	v_fma_f32 v245, -v45, v45, 1.0
	v_fma_f32 v246, -v46, v46, 1.0
	v_fma_f32 v247, -v47, v47, 1.0
	v_sqrt_f32_e32 v244, v244
	v_sqrt_f32_e32 v245, v245
	v_sqrt_f32_e32 v246, v246
	v_sqrt_f32_e32 v247, v247
	v_lshlrev_b32_e32 v239, 16, v239
	v_lshlrev_b32_e32 v240, 16, v240
	v_lshlrev_b32_e32 v241, 16, v241
	v_lshlrev_b32_e32 v242, 16, v242
	v_mul_f32_e32 v244, v244, v60
	v_mul_f32_e32 v245, v245, v61
	v_mul_f32_e32 v246, v246, v62
	v_mul_f32_e32 v247, v247, v63
	v_mul_f32_e32 v239, v244, v239
	v_mul_f32_e32 v240, v245, v240
	v_mul_f32_e32 v63, v246, v241
	v_mul_f32_e32 v241, v247, v242
	v_mov_b32_e32 v227, v32
	v_fmac_f32_e32 v49, 0, v32
	v_fmac_f32_e32 v228, v33, v49
	v_mul_f32_e32 v50, v227, v33
	v_fmac_f32_e32 v229, v34, v228
	v_mul_f32_e32 v51, v50, v34
	v_fmac_f32_e32 v230, v35, v229
	v_mul_f32_e32 v52, v51, v35
	v_fmac_f32_e32 v231, v36, v230
	v_mul_f32_e32 v53, v52, v36
	v_fmac_f32_e32 v232, v37, v231
	v_mul_f32_e32 v54, v53, v37
	v_fmac_f32_e32 v233, v38, v232
	v_mul_f32_e32 v55, v54, v38
	v_fmac_f32_e32 v234, v39, v233
	v_mul_f32_e32 v56, v55, v39
	v_fmac_f32_e32 v235, v40, v234
	v_mul_f32_e32 v57, v56, v40
	v_fmac_f32_e32 v236, v41, v235
	v_mul_f32_e32 v58, v57, v41
	v_fmac_f32_e32 v237, v42, v236
	v_mul_f32_e32 v59, v58, v42
	v_fmac_f32_e32 v238, v43, v237
	v_mul_f32_e32 v60, v59, v43
	v_fmac_f32_e32 v239, v44, v238
	v_mul_f32_e32 v61, v60, v44
	v_fmac_f32_e32 v240, v45, v239
	v_mul_f32_e32 v62, v61, v45
	v_fmac_f32_e32 v63, v46, v240
	v_mul_f32_e32 v243, v62, v46
	v_fmac_f32_e32 v241, v47, v63
	v_mul_f32_e32 v242, v243, v47
	v_mov_b32_e32 v244, v242
	v_mov_b32_e32 v246, v242
	v_mov_b32_e32 v245, v241
	v_mov_b32_e32 v247, v241
	s_nop 1
	v_permlane32_swap_b32 v244, v246
	v_permlane32_swap_b32 v245, v247
	s_and_saveexec_b64 s[18:19], vcc
	s_cbranch_execz .LBB0_313
	v_fma_f32 v32, v246, v245, v247
	v_mul_f32_e32 v33, v244, v246
	v_add_u32_e32 v35, s98, v254
	ds_write2_b32 v35, v33, v32 offset1:32
; #define LAS __attribute__((address_space(3)))
; __device__ __forceinline__ unsigned cvt_pk_bf16(float lo, float hi) { unsigned r; asm volatile("v_cvt_pk_bf16_f32 %0, %1, %2" : "=v"(r) : "v"(lo), "v"(hi)); return r; }
; __device__ __forceinline__ float bf_lo(unsigned u) { return __uint_as_float(u << 16); }
; __device__ __forceinline__ float bf_hi(unsigned u) { return __uint_as_float(u & 0xffff0000u); }
; __device__ __forceinline__ bf16_t f2bf(float f) { return (bf16_t)(cvt_pk_bf16(f, 0.f) & 0xffffu); }
; #define LDS_BARRIER() do { asm volatile("s_waitcnt lgkmcnt(0)" ::: "memory"); __builtin_amdgcn_s_barrier(); asm volatile("" ::: "memory"); } while (0)
; template <int dir>
; __device__ __forceinline__ void lru_pass(LAS unsigned char* lds, const Params& P, int b, int h, int q, bool dry) {
;     ...
;             LDS_BARRIER();
;             float cin = carry, cend = carry;
; #pragma unroll
;             for (int w = 0; w < 8; ++w) { const float pw = AGG[(w * 2 + 0) * 32 + nl], ew = AGG[(w * 2 + 1) * 32 + nl]; if (w == wid) cin = cend; cend = fmaf(pw, cend, ew); }
;             carry = cend;
;             if (g) cin = fmaf(P0, cin, E0);
;             if (!isctx) {
; #pragma unroll
;                 for (int v = 0; v < 16; ++v) { const float hv = fmaf(zi[v], cin, zr[v]);
;                     const int s = sbase + v; const int tl = dir == 0 ? s : 255 - s;
;                     if (dir == 0) *(LAS unsigned*)(TOUT + tl * IO_WP + nl * 4) = (cvt_pk_bf16(hv, 0.f) & 0xffffu) | (pk[v] << 16);
;                     else *(LAS bf16_t*)(TOUT + tl * IO_NP + nl * 2) = f2bf((bf_lo(pk[v]) + hv) * bf_hi(pk[v])); }
;             }
.LBB0_313:
	s_or_b64 exec, exec, s[18:19]
	s_waitcnt lgkmcnt(0)
	s_barrier
	s_setprio 1
	v_add_u32_e32 v34, s99, v161
	ds_read2_b32 v[36:37], v34 offset1:32
	ds_read2_b32 v[38:39], v34 offset0:64 offset1:96
	ds_read2_b32 v[40:41], v34 offset0:128 offset1:160
	ds_read2_b32 v[42:43], v34 offset0:192 offset1:224
	v_add_u32_e32 v32, s100, v161
	s_waitcnt lgkmcnt(3)
	v_fmac_f32_e32 v37, v36, v222
	s_waitcnt lgkmcnt(2)
	v_fmac_f32_e32 v39, v38, v37
	s_waitcnt lgkmcnt(1)
	v_fmac_f32_e32 v41, v40, v39
	ds_read2_b32 v[44:45], v32 offset1:32
	ds_read2_b32 v[46:47], v32 offset0:64 offset1:96
	ds_read2_b32 v[34:35], v32 offset0:128 offset1:160
	ds_read2_b32 v[32:33], v32 offset0:192 offset1:224
	s_waitcnt lgkmcnt(4)
	v_fmac_f32_e32 v43, v42, v41
	s_waitcnt lgkmcnt(3)
	v_fmac_f32_e32 v45, v44, v43
	s_waitcnt lgkmcnt(2)
	v_fmac_f32_e32 v47, v46, v45
	s_cmp_eq_u32 s44, 0
	s_waitcnt lgkmcnt(1)
	v_fmac_f32_e32 v35, v34, v47
	s_cbranch_scc1 .LBB0_315
	v_cndmask_b32_e64 v37, v222, v37, s[14:15]
	v_cndmask_b32_e64 v37, v37, v39, s[12:13]
	v_cndmask_b32_e64 v37, v37, v41, s[10:11]
	v_cndmask_b32_e64 v37, v37, v43, s[8:9]
	v_cndmask_b32_e64 v37, v37, v45, s[4:5]
	v_cndmask_b32_e64 v37, v37, v47, s[16:17]
	v_cndmask_b32_e64 v37, v37, v35, s[0:1]
	v_fmac_f32_e32 v245, v244, v37
	v_cndmask_b32_e32 v34, v245, v37, vcc
	v_fmac_f32_e32 v49, v227, v34
	v_fmac_f32_e32 v228, v50, v34
	v_fmac_f32_e32 v229, v51, v34
	v_fmac_f32_e32 v230, v52, v34
	v_fmac_f32_e32 v231, v53, v34
	v_fmac_f32_e32 v232, v54, v34
	v_fmac_f32_e32 v233, v55, v34
	v_fmac_f32_e32 v234, v56, v34
	v_fmac_f32_e32 v235, v57, v34
	v_fmac_f32_e32 v236, v58, v34
	v_fmac_f32_e32 v237, v59, v34
	v_fmac_f32_e32 v238, v60, v34
	v_fmac_f32_e32 v239, v61, v34
	v_fmac_f32_e32 v240, v62, v34
	v_fmac_f32_e32 v63, v243, v34
	v_fmac_f32_e32 v241, v242, v34
	v_lshlrev_b32_e32 v36, 16, v226
	v_lshlrev_b32_e32 v38, 16, v225
	v_add_f32_e32 v36, v49, v36
	v_add_f32_e32 v38, v228, v38
	v_and_b32_e32 v37, 0xffff0000, v226
	v_and_b32_e32 v39, 0xffff0000, v225
	v_mul_f32_e32 v36, v36, v37
	v_mul_f32_e32 v38, v38, v39
	v_cvt_pk_bf16_f32 v36, v36, v38
	ds_write_b16 v206, v36
	ds_write_b16_d16_hi v207, v36
	v_lshlrev_b32_e32 v40, 16, v224
	v_lshlrev_b32_e32 v42, 16, v223
	v_add_f32_e32 v40, v229, v40
	v_add_f32_e32 v42, v230, v42
	v_and_b32_e32 v41, 0xffff0000, v224
	v_and_b32_e32 v43, 0xffff0000, v223
	v_mul_f32_e32 v40, v40, v41
	v_mul_f32_e32 v42, v42, v43
	v_cvt_pk_bf16_f32 v40, v40, v42
	ds_write_b16 v208, v40
	ds_write_b16_d16_hi v209, v40
	v_lshlrev_b32_e32 v36, 16, v135
	v_lshlrev_b32_e32 v38, 16, v134
	v_add_f32_e32 v36, v231, v36
	v_add_f32_e32 v38, v232, v38
	v_and_b32_e32 v37, 0xffff0000, v135
	v_and_b32_e32 v39, 0xffff0000, v134
	v_mul_f32_e32 v36, v36, v37
	v_mul_f32_e32 v38, v38, v39
	v_cvt_pk_bf16_f32 v36, v36, v38
	ds_write_b16 v210, v36
	ds_write_b16_d16_hi v211, v36
	v_lshlrev_b32_e32 v40, 16, v133
	v_lshlrev_b32_e32 v42, 16, v131
	v_add_f32_e32 v40, v233, v40
	v_add_f32_e32 v42, v234, v42
	v_and_b32_e32 v41, 0xffff0000, v133
	v_and_b32_e32 v43, 0xffff0000, v131
	v_mul_f32_e32 v40, v40, v41
	v_mul_f32_e32 v42, v42, v43
	v_cvt_pk_bf16_f32 v40, v40, v42
	ds_write_b16 v212, v40
	ds_write_b16_d16_hi v213, v40
	v_lshlrev_b32_e32 v36, 16, v132
	v_lshlrev_b32_e32 v38, 16, v130
	v_add_f32_e32 v36, v235, v36
	v_add_f32_e32 v38, v236, v38
	v_and_b32_e32 v37, 0xffff0000, v132
	v_and_b32_e32 v39, 0xffff0000, v130
	v_mul_f32_e32 v36, v36, v37
	v_mul_f32_e32 v38, v38, v39
	v_cvt_pk_bf16_f32 v36, v36, v38
	ds_write_b16 v214, v36
	ds_write_b16_d16_hi v215, v36
	v_lshlrev_b32_e32 v40, 16, v129
	v_lshlrev_b32_e32 v42, 16, v128
	v_add_f32_e32 v40, v237, v40
	v_add_f32_e32 v42, v238, v42
	v_and_b32_e32 v41, 0xffff0000, v129
	v_and_b32_e32 v43, 0xffff0000, v128
	v_mul_f32_e32 v40, v40, v41
	v_mul_f32_e32 v42, v42, v43
	v_cvt_pk_bf16_f32 v40, v40, v42
	ds_write_b16 v216, v40
	ds_write_b16_d16_hi v217, v40
	v_lshlrev_b32_e32 v36, 16, v67
	v_lshlrev_b32_e32 v38, 16, v66
	v_add_f32_e32 v36, v239, v36
	v_add_f32_e32 v38, v240, v38
	v_and_b32_e32 v37, 0xffff0000, v67
	v_and_b32_e32 v39, 0xffff0000, v66
	v_mul_f32_e32 v36, v36, v37
	v_mul_f32_e32 v38, v38, v39
	v_cvt_pk_bf16_f32 v36, v36, v38
	ds_write_b16 v218, v36
	ds_write_b16_d16_hi v219, v36
	v_lshlrev_b32_e32 v40, 16, v64
	v_lshlrev_b32_e32 v42, 16, v251
	v_add_f32_e32 v40, v63, v40
	v_add_f32_e32 v42, v241, v42
	v_and_b32_e32 v41, 0xffff0000, v64
	v_and_b32_e32 v43, 0xffff0000, v251
	v_mul_f32_e32 v40, v40, v41
	v_mul_f32_e32 v42, v42, v43
	v_cvt_pk_bf16_f32 v40, v40, v42
	ds_write_b16 v220, v40
	ds_write_b16_d16_hi v221, v40
